# fox fast path v2: QK(mi1) MFMAs interleaved with mi0 VALU, overflow check on row sums instead of max chain
# speedup vs baseline: 1.0090x; 1.0090x over previous
; DI float ex2(float x) { return __builtin_amdgcn_exp2f(x); }
; DI f32x4 mmaT(bf16x8 a_m, bf16x8 b_n, f32x4 c) { return __builtin_amdgcn_mfma_f32_16x16x32_bf16(b_n, a_m, c, 0, 0, 0); }
; template <bool DIAG>
; DI void fox_tile(const bf16_t* sK, const bf16_t* sV, const float* sFk, const bf16x8 (&qf)[2][2], f32x4 (&o)[2][4], float (&mrun)[2], float (&lsum)[2], int key0, int qg0, int fr, int fq, int lane) {
;   const float SC2 = 0.125f * LOG2E;
;   f32x4 s[2][4];
;   const int kof = (fr * 64 + fq * 16) ^ ((fr >> 3) << 5);
; #pragma unroll
;   for (int t = 0; t < 4; ++t) {
;     const bf16x8 k0 = *(const bf16x8*)((const unsigned char*)sK + (t * 2) * 1024 + kof), k1 = *(const bf16x8*)((const unsigned char*)sK + (t * 2 + 1) * 1024 + kof);
; #pragma unroll
;     for (int mi = 0; mi < 2; ++mi) { s[mi][t] = mmaT(qf[mi][0], k0, (f32x4){0.f, 0.f, 0.f, 0.f}); s[mi][t] = mmaT(qf[mi][1], k1, s[mi][t]); }
;   }
;   f32x4 fk[4];
; #pragma unroll
;   for (int t = 0; t < 4; ++t) fk[t] = *(const f32x4*)(sFk + 16 * t + 4 * fq);
;   __builtin_amdgcn_sched_barrier(0);
;   bf16x8 vf[2][4];
; #pragma unroll
;   for (int k2 = 0; k2 < 2; ++k2)
; #pragma unroll
;     for (int d = 0; d < 4; ++d) {
;       const bf16_t* a = sV + (32 * k2 + 4 * fq + (fr >> 2)) * 72 + 16 * d + 4 * (fr & 3);
;       const v4i16_t lo = tr_rd(a), hi = tr_rd(a + 16 * 72);
;       vf[k2][d] = __builtin_shufflevector(lo, hi, 0, 1, 2, 3, 4, 5, 6, 7);
;     }
;   __builtin_amdgcn_sched_barrier(0);
; #pragma unroll
;   for (int mi = 0; mi < 2; ++mi) {
;     float mx = -INFINITY;
; #pragma unroll
;     for (int t = 0; t < 4; ++t)
; #pragma unroll
;       for (int j = 0; j < 4; ++j) {
;         float x = __builtin_fmaf(s[mi][t][j], SC2, fk[t][j]);
;         if (DIAG) { if (key0 + 16 * t + 4 * fq + j > qg0 + 16 * mi) x = -INFINITY; }
;         s[mi][t][j] = x; mx = fmaxf(mx, x);
;       }
;     mx = fmaxf(mx, shx(mx, 16, lane)); mx = fmaxf(mx, shx(mx, 32, lane));
;     const float mnew = fmaxf(mrun[mi], mx), alpha = ex2(mrun[mi] - mnew);
;     mrun[mi] = mnew;
;     float ps = 0.f;
; #pragma unroll
;     for (int t = 0; t < 4; ++t)
; #pragma unroll
;       for (int j = 0; j < 4; ++j) { const float pv = ex2(s[mi][t][j] - mnew); s[mi][t][j] = pv; ps += pv; }
;     lsum[mi] = lsum[mi] * alpha + ps;
; #pragma unroll
;     for (int d = 0; d < 4; ++d) o[mi][d] *= alpha;
;   }
.LBB0_491:
	s_andn2_b64 vcc, exec, s[4:5]
	s_cbranch_vccnz .LBB0_493
	s_waitcnt lgkmcnt(11)
	v_mfma_f32_16x16x32_bf16 v[72:75], v[64:67], v[0:3], v[224:227]
	s_waitcnt lgkmcnt(10)
	v_mfma_f32_16x16x32_bf16 v[72:75], v[68:71], v[4:7], v[72:75]
	s_waitcnt lgkmcnt(9)
	v_mfma_f32_16x16x32_bf16 v[76:79], v[56:59], v[0:3], v[224:227]
	s_waitcnt lgkmcnt(8)
	v_mfma_f32_16x16x32_bf16 v[76:79], v[60:63], v[4:7], v[76:79]
	s_waitcnt lgkmcnt(7)
	v_mfma_f32_16x16x32_bf16 v[80:83], v[48:51], v[0:3], v[224:227]
	s_waitcnt lgkmcnt(6)
	v_mfma_f32_16x16x32_bf16 v[80:83], v[52:55], v[4:7], v[80:83]
	s_waitcnt lgkmcnt(5)
	v_mfma_f32_16x16x32_bf16 v[96:99], v[40:43], v[0:3], v[224:227]
	s_waitcnt lgkmcnt(4)
	v_mfma_f32_16x16x32_bf16 v[96:99], v[44:47], v[4:7], v[96:99]
	s_waitcnt lgkmcnt(0)
	v_mfma_f32_16x16x32_bf16 v[84:87], v[64:67], v[8:11], v[228:231]
	v_mfma_f32_16x16x32_bf16 v[84:87], v[68:71], v[12:15], v[84:87]
	v_fmamk_f32 v72, v72, 0x3e38aa3b, v36
	v_fmamk_f32 v73, v73, 0x3e38aa3b, v37
	v_fmamk_f32 v74, v74, 0x3e38aa3b, v38
	v_fmamk_f32 v75, v75, 0x3e38aa3b, v39
	v_mfma_f32_16x16x32_bf16 v[88:91], v[56:59], v[8:11], v[228:231]
	v_mfma_f32_16x16x32_bf16 v[88:91], v[60:63], v[12:15], v[88:91]
	v_fmamk_f32 v76, v76, 0x3e38aa3b, v32
	v_fmamk_f32 v77, v77, 0x3e38aa3b, v33
	v_fmamk_f32 v78, v78, 0x3e38aa3b, v34
	v_fmamk_f32 v79, v79, 0x3e38aa3b, v35
	v_mfma_f32_16x16x32_bf16 v[92:95], v[48:51], v[8:11], v[228:231]
	v_mfma_f32_16x16x32_bf16 v[92:95], v[52:55], v[12:15], v[92:95]
	v_fmamk_f32 v80, v80, 0x3e38aa3b, v28
	v_fmamk_f32 v81, v81, 0x3e38aa3b, v29
	v_fmamk_f32 v82, v82, 0x3e38aa3b, v30
	v_fmamk_f32 v83, v83, 0x3e38aa3b, v31
	v_mfma_f32_16x16x32_bf16 v[164:167], v[40:43], v[8:11], v[228:231]
	v_mfma_f32_16x16x32_bf16 v[164:167], v[44:47], v[12:15], v[164:167]
	v_fmamk_f32 v96, v96, 0x3e38aa3b, v24
	v_fmamk_f32 v97, v97, 0x3e38aa3b, v25
	v_fmamk_f32 v98, v98, 0x3e38aa3b, v26
	v_fmamk_f32 v99, v99, 0x3e38aa3b, v27
	ds_read_b64_tr_b16 v[68:69], v221 offset:9216
	ds_read_b64_tr_b16 v[60:61], v221 offset:9248
	ds_read_b64_tr_b16 v[64:65], v221 offset:9280
	ds_read_b64_tr_b16 v[56:57], v221 offset:9312
	ds_read_b64_tr_b16 v[70:71], v221 offset:11520
	ds_read_b64_tr_b16 v[62:63], v221 offset:11552
	ds_read_b64_tr_b16 v[66:67], v221 offset:11584
	ds_read_b64_tr_b16 v[58:59], v221 offset:11616
	ds_read_b64_tr_b16 v[52:53], v221 offset:13824
	ds_read_b64_tr_b16 v[48:49], v221 offset:13856
	ds_read_b64_tr_b16 v[44:45], v221 offset:13888
	ds_read_b64_tr_b16 v[40:41], v221 offset:13920
	ds_read_b64_tr_b16 v[54:55], v221 offset:16128
	ds_read_b64_tr_b16 v[50:51], v221 offset:16160
	ds_read_b64_tr_b16 v[46:47], v221 offset:16192
	ds_read_b64_tr_b16 v[42:43], v221 offset:16224
	v_exp_f32_e32 v72, v72
	v_exp_f32_e32 v73, v73
	v_exp_f32_e32 v74, v74
	v_exp_f32_e32 v75, v75
	v_exp_f32_e32 v76, v76
	v_exp_f32_e32 v77, v77
	v_exp_f32_e32 v78, v78
	v_exp_f32_e32 v79, v79
	v_exp_f32_e32 v80, v80
	v_exp_f32_e32 v81, v81
	v_exp_f32_e32 v82, v82
	v_exp_f32_e32 v83, v83
	v_exp_f32_e32 v96, v96
	v_exp_f32_e32 v97, v97
	v_exp_f32_e32 v98, v98
	v_exp_f32_e32 v99, v99
	v_fmamk_f32 v84, v84, 0x3e38aa3b, v36
	v_fmamk_f32 v85, v85, 0x3e38aa3b, v37
	v_fmamk_f32 v86, v86, 0x3e38aa3b, v38
	v_fmamk_f32 v87, v87, 0x3e38aa3b, v39
	v_fmamk_f32 v88, v88, 0x3e38aa3b, v32
	v_fmamk_f32 v89, v89, 0x3e38aa3b, v33
	v_fmamk_f32 v90, v90, 0x3e38aa3b, v34
	v_fmamk_f32 v91, v91, 0x3e38aa3b, v35
	v_fmamk_f32 v92, v92, 0x3e38aa3b, v28
	v_fmamk_f32 v93, v93, 0x3e38aa3b, v29
	v_fmamk_f32 v94, v94, 0x3e38aa3b, v30
	v_fmamk_f32 v95, v95, 0x3e38aa3b, v31
	v_fmamk_f32 v164, v164, 0x3e38aa3b, v24
	v_fmamk_f32 v165, v165, 0x3e38aa3b, v25
	v_fmamk_f32 v166, v166, 0x3e38aa3b, v26
	v_fmamk_f32 v167, v167, 0x3e38aa3b, v27
	v_add_f32_e32 v146, v72, v73
	v_add_f32_e32 v147, v74, v75
	v_add_f32_e32 v148, v76, v77
	v_add_f32_e32 v149, v78, v79
	v_add_f32_e32 v150, v80, v81
	v_add_f32_e32 v151, v82, v83
	v_add_f32_e32 v152, v96, v97
	v_add_f32_e32 v153, v98, v99
	v_add_f32_e32 v146, v146, v147
	v_add_f32_e32 v147, v148, v149
	v_add_f32_e32 v148, v150, v151
	v_add_f32_e32 v149, v152, v153
	v_add_f32_e32 v146, v146, v147
	v_add_f32_e32 v148, v148, v149
	v_add_f32_e32 v146, v146, v148
	v_exp_f32_e32 v84, v84
	v_exp_f32_e32 v85, v85
	v_exp_f32_e32 v86, v86
	v_exp_f32_e32 v87, v87
	v_exp_f32_e32 v88, v88
	v_exp_f32_e32 v89, v89
	v_exp_f32_e32 v90, v90
	v_exp_f32_e32 v91, v91
	v_exp_f32_e32 v92, v92
	v_exp_f32_e32 v93, v93
	v_exp_f32_e32 v94, v94
	v_exp_f32_e32 v95, v95
	v_exp_f32_e32 v164, v164
	v_exp_f32_e32 v165, v165
	v_exp_f32_e32 v166, v166
	v_exp_f32_e32 v167, v167
	v_add_f32_e32 v148, v84, v85
	v_add_f32_e32 v149, v86, v87
	v_add_f32_e32 v150, v88, v89
	v_add_f32_e32 v151, v90, v91
	v_add_f32_e32 v152, v92, v93
	v_add_f32_e32 v153, v94, v95
	v_add_f32_e32 v154, v164, v165
	v_add_f32_e32 v155, v166, v167
	v_add_f32_e32 v148, v148, v149
	v_add_f32_e32 v149, v150, v151
	v_add_f32_e32 v150, v152, v153
	v_add_f32_e32 v151, v154, v155
	v_add_f32_e32 v148, v148, v149
	v_add_f32_e32 v150, v150, v151
	v_add_f32_e32 v148, v148, v150
	v_max_f32_e32 v147, v146, v148
	v_cmp_lt_f32_e32 vcc, 0x69800000, v147
	s_cbranch_vccnz .Lfox1_fallback
	v_add_f32_e32 v128, v128, v146
	v_add_f32_e32 v129, v129, v148
	v_cvt_pk_bf16_f32 v36, v72, v73
	v_cvt_pk_bf16_f32 v37, v74, v75
	v_cvt_pk_bf16_f32 v38, v76, v77
	v_cvt_pk_bf16_f32 v39, v78, v79
	v_cvt_pk_bf16_f32 v28, v80, v81
	v_cvt_pk_bf16_f32 v29, v82, v83
	v_cvt_pk_bf16_f32 v30, v96, v97
	v_cvt_pk_bf16_f32 v31, v98, v99
	s_cmp_eq_u32 s99, 0
	s_cbranch_scc1 .Lfox1_nm2
	s_barrier
; DI unsigned pk2(float lo, float hi) { unsigned r; asm volatile("v_cvt_pk_bf16_f32 %0, %1, %2" : "=v"(r) : "v"(lo), "v"(hi)); return r; }
; DI f32x4 mmaT(bf16x8 a_m, bf16x8 b_n, f32x4 c) { return __builtin_amdgcn_mfma_f32_16x16x32_bf16(b_n, a_m, c, 0, 0, 0); }
; template <bool DIAG>
; DI void fox_tile(const bf16_t* sK, const bf16_t* sV, const float* sFk, const bf16x8 (&qf)[2][2], f32x4 (&o)[2][4], float (&mrun)[2], float (&lsum)[2], int key0, int qg0, int fr, int fq, int lane) {
;     ...
;   for (int t = 0; t < 4; ++t) {
;     const bf16x8 k0 = *(const bf16x8*)((const unsigned char*)sK + (t * 2) * 1024 + kof), k1 = *(const bf16x8*)((const unsigned char*)sK + (t * 2 + 1) * 1024 + kof);
; #pragma unroll
;     for (int mi = 0; mi < 2; ++mi) { s[mi][t] = mmaT(qf[mi][0], k0, (f32x4){0.f, 0.f, 0.f, 0.f}); s[mi][t] = mmaT(qf[mi][1], k1, s[mi][t]); }
;     ...
; #pragma unroll
;   for (int k2 = 0; k2 < 2; ++k2) {
;     bf16x8 pa[2];
; #pragma unroll
;     for (int mi = 0; mi < 2; ++mi) pa[mi] = mk8(pk2(s[mi][2 * k2][0], s[mi][2 * k2][1]), pk2(s[mi][2 * k2][2], s[mi][2 * k2][3]), pk2(s[mi][2 * k2 + 1][0], s[mi][2 * k2 + 1][1]), pk2(s[mi][2 * k2 + 1][2], s[mi][2 * k2 + 1][3]));
; #pragma unroll
;     for (int d = 0; d < 4; ++d) {
; #pragma unroll
;       for (int mi = 0; mi < 2; ++mi) o[mi][d] = mmaT(pa[mi], vf[k2][d], o[mi][d]);
;     }
;   }
.Lfox1_nm2:
	s_waitcnt lgkmcnt(8)
	v_mfma_f32_16x16x32_bf16 v[142:145], v[68:71], v[36:39], v[142:145]
	v_cvt_pk_bf16_f32 v32, v84, v85
	v_mfma_f32_16x16x32_bf16 v[138:141], v[60:63], v[36:39], v[138:141]
	v_cvt_pk_bf16_f32 v33, v86, v87
	v_mfma_f32_16x16x32_bf16 v[134:137], v[64:67], v[36:39], v[134:137]
	v_cvt_pk_bf16_f32 v34, v88, v89
	v_mfma_f32_16x16x32_bf16 v[130:133], v[56:59], v[36:39], v[130:133]
	v_cvt_pk_bf16_f32 v35, v90, v91
	s_waitcnt lgkmcnt(0)
	v_mfma_f32_16x16x32_bf16 v[142:145], v[52:55], v[28:31], v[142:145]
	v_cvt_pk_bf16_f32 v24, v92, v93
	v_mfma_f32_16x16x32_bf16 v[138:141], v[48:51], v[28:31], v[138:141]
	v_cvt_pk_bf16_f32 v25, v94, v95
	v_mfma_f32_16x16x32_bf16 v[134:137], v[44:47], v[28:31], v[134:137]
	v_cvt_pk_bf16_f32 v26, v164, v165
	v_mfma_f32_16x16x32_bf16 v[130:133], v[40:43], v[28:31], v[130:133]
	v_cvt_pk_bf16_f32 v27, v166, v167
	s_nop 1
	v_mfma_f32_16x16x32_bf16 v[122:125], v[68:71], v[32:35], v[122:125]
	v_mfma_f32_16x16x32_bf16 v[118:121], v[60:63], v[32:35], v[118:121]
	v_mfma_f32_16x16x32_bf16 v[114:117], v[64:67], v[32:35], v[114:117]
	v_mfma_f32_16x16x32_bf16 v[110:113], v[56:59], v[32:35], v[110:113]
	v_mfma_f32_16x16x32_bf16 v[122:125], v[52:55], v[24:27], v[122:125]
	v_mfma_f32_16x16x32_bf16 v[118:121], v[48:51], v[24:27], v[118:121]
	v_mfma_f32_16x16x32_bf16 v[114:117], v[44:47], v[24:27], v[114:117]
	v_mfma_f32_16x16x32_bf16 v[110:113], v[40:43], v[24:27], v[110:113]
	s_branch .Lfox1_join
.Lfox1_fallback:
	s_mul_i32 s4, s21, 0x4900
	s_add_i32 s4, s4, 32
	v_add_u32_e32 v146, s4, v213
	ds_read_b128 v[64:67], v146
	ds_read_b128 v[68:71], v146 offset:1024
	ds_read_b128 v[56:59], v146 offset:2048
	ds_read_b128 v[60:63], v146 offset:3072
	ds_read_b128 v[48:51], v146 offset:4096
	ds_read_b128 v[52:55], v146 offset:5120
	ds_read_b128 v[40:43], v146 offset:6144
	ds_read_b128 v[44:47], v146 offset:7168
	s_waitcnt lgkmcnt(0)

; DI f32x4 mmaT(bf16x8 a_m, bf16x8 b_n, f32x4 c) { return __builtin_amdgcn_mfma_f32_16x16x32_bf16(b_n, a_m, c, 0, 0, 0); }
; template <bool DIAG>
; DI void fox_tile(const bf16_t* sK, const bf16_t* sV, const float* sFk, const bf16x8 (&qf)[2][2], f32x4 (&o)[2][4], float (&mrun)[2], float (&lsum)[2], int key0, int qg0, int fr, int fq, int lane) {
;     ...
;   for (int t = 0; t < 4; ++t) {
;     const bf16x8 k0 = *(const bf16x8*)((const unsigned char*)sK + (t * 2) * 1024 + kof), k1 = *(const bf16x8*)((const unsigned char*)sK + (t * 2 + 1) * 1024 + kof);
; #pragma unroll
;     for (int mi = 0; mi < 2; ++mi) { s[mi][t] = mmaT(qf[mi][0], k0, (f32x4){0.f, 0.f, 0.f, 0.f}); s[mi][t] = mmaT(qf[mi][1], k1, s[mi][t]); }
.Lfox2_fallback:
	s_mul_i32 s4, s20, 0x4900
	s_add_i32 s4, s4, 32
	v_add_u32_e32 v146, s4, v213
	ds_read_b128 v[64:67], v146
	ds_read_b128 v[68:71], v146 offset:1024
	ds_read_b128 v[56:59], v146 offset:2048
	ds_read_b128 v[60:63], v146 offset:3072
	ds_read_b128 v[48:51], v146 offset:4096
	ds_read_b128 v[52:55], v146 offset:5120
	ds_read_b128 v[40:43], v146 offset:6144
	ds_read_b128 v[44:47], v146 offset:7168
	s_waitcnt lgkmcnt(0)
